# rewrote the SwiGLU epilogue body: row-sum records loaded up front, packed f32 ops, no hazard nops; same per-element operation order
# speedup vs baseline: 1.0065x; 1.0065x over previous
.LBB0_518:
	v_readlane_b32 s10, v254, 26
	s_waitcnt lgkmcnt(0)
	s_add_u32 s10, s12, s10
	v_readlane_b32 s11, v254, 25
	s_addc_u32 s11, s13, s11
	v_readlane_b32 s17, v254, 50
	s_add_u32 s17, s10, s17
	s_addc_u32 s52, s11, 0
	s_add_u32 s10, s12, 0x8000000
	s_addc_u32 s11, s13, 0
	s_lshl_b64 s[14:15], s[14:15], 2
	s_add_u32 s17, s17, s14
	s_addc_u32 s52, s52, s15
	s_lshl_b32 s14, s16, 8
	s_ashr_i32 s15, s14, 31
	s_lshl_b64 s[14:15], s[14:15], 2
	s_add_u32 s14, s17, s14
	s_addc_u32 s15, s52, s15
	v_readlane_b32 s52, v254, 11
	s_lshl_b32 s17, s52, 2
	s_add_u32 s14, s14, s17
	s_addc_u32 s15, s15, 0
	v_lshlrev_b32_e32 v0, 2, v184
	v_lshl_add_u64 v[130:131], s[14:15], 0, v[0:1]
	s_mov_b64 s[14:15], 0xb00000
	v_lshl_add_u32 v150, s34, 8, v241
	v_lshl_add_u64 v[132:133], v[130:131], 0, s[14:15]
	s_mov_b32 s14, 0xb00000
	v_ashrrev_i32_e32 v151, 31, v150
	v_add_co_u32_e32 v130, vcc, s14, v130
	v_lshl_add_u64 v[146:147], v[150:151], 4, s[12:13]
	s_mov_b64 s[12:13], 0xa00000
	v_addc_co_u32_e32 v131, vcc, 0, v131, vcc
	v_lshl_add_u64 v[154:155], v[146:147], 0, s[12:13]
	s_mov_b32 s12, 0xa00000
	v_add_co_u32_e32 v146, vcc, s12, v146
	global_load_dwordx4 v[142:145], v[130:131], off
	global_load_dwordx4 v[138:141], v[132:133], off offset:64
	global_load_dwordx4 v[134:137], v[132:133], off offset:512
	s_nop 0
	global_load_dwordx4 v[130:133], v[132:133], off offset:576
	v_addc_co_u32_e32 v147, vcc, 0, v147, vcc
	global_load_dwordx4 v[146:149], v[146:147], off
	global_load_dwordx4 v[200:203], v[154:155], off offset:256
	global_load_dwordx4 v[204:207], v[154:155], off offset:512
	global_load_dwordx4 v[208:211], v[154:155], off offset:768
	global_load_dwordx4 v[212:215], v[154:155], off offset:2048
	global_load_dwordx4 v[216:219], v[154:155], off offset:2304
	global_load_dwordx4 v[220:223], v[154:155], off offset:2560
	global_load_dwordx4 v[224:227], v[154:155], off offset:2816
	v_mov_b32_e32 v0, v150
	s_movk_i32 s14, 0x1600
	s_lshl_b32 s70, s52, 1
	s_waitcnt vmcnt(0)
	v_mov_b64_e32 v[152:153], s[10:11]
	v_mad_i64_i32 v[164:165], s[12:13], v150, s14, v[152:153]
	s_lshl_b32 s10, s16, 7
	s_ashr_i32 s11, s10, 31
	s_lshl_b64 s[10:11], s[10:11], 1
	v_lshl_add_u64 v[164:165], v[164:165], 0, s[10:11]
	v_lshl_add_u64 v[164:165], v[164:165], 0, s[70:71]
	v_lshlrev_b32_e32 v0, 1, v182
	v_lshl_add_u64 v[164:165], v[164:165], 0, v[0:1]
	s_mov_b64 s[12:13], 0x16000
	s_mov_b64 s[14:15], 0x6e000
	s_mov_b32 s10, 0xbfb8aa3b
	s_mov_b32 s11, 0xbfb8aa3b
	v_add_f32_e32 v166, v146, v147
	v_add_f32_e32 v167, v148, v149
	v_add_f32_e32 v166, v166, v167
	v_fmamk_f32 v166, v166, 0x3a800000, v231
	v_rsq_f32_e32 v166, v166
	s_nop 0
	v_pk_fma_f32 v[30:31], v[30:31], v[166:167], v[142:143] op_sel_hi:[1,0,1]
	v_pk_fma_f32 v[32:33], v[32:33], v[166:167], v[144:145] op_sel_hi:[1,0,1]
	v_pk_fma_f32 v[22:23], v[22:23], v[166:167], v[134:135] op_sel_hi:[1,0,1]
	v_pk_fma_f32 v[24:25], v[24:25], v[166:167], v[136:137] op_sel_hi:[1,0,1]
	v_pk_fma_f32 v[26:27], v[26:27], v[166:167], v[138:139] op_sel_hi:[1,0,1]
	v_pk_fma_f32 v[28:29], v[28:29], v[166:167], v[140:141] op_sel_hi:[1,0,1]
	v_pk_fma_f32 v[14:15], v[14:15], v[166:167], v[130:131] op_sel_hi:[1,0,1]
	v_pk_fma_f32 v[16:17], v[16:17], v[166:167], v[132:133] op_sel_hi:[1,0,1]
	v_pk_mul_f32 v[168:169], v[30:31], s[10:11] op_sel_hi:[1,0]
	v_pk_mul_f32 v[170:171], v[32:33], s[10:11] op_sel_hi:[1,0]
	v_pk_mul_f32 v[172:173], v[22:23], s[10:11] op_sel_hi:[1,0]
	v_pk_mul_f32 v[174:175], v[24:25], s[10:11] op_sel_hi:[1,0]
	v_exp_f32_e32 v168, v168
	v_exp_f32_e32 v169, v169
	v_exp_f32_e32 v170, v170
	v_exp_f32_e32 v171, v171
	v_exp_f32_e32 v172, v172
	v_exp_f32_e32 v173, v173
	v_exp_f32_e32 v174, v174
	v_exp_f32_e32 v175, v175
	v_pk_add_f32 v[168:169], v[168:169], 1.0 op_sel_hi:[1,0]
	v_pk_add_f32 v[170:171], v[170:171], 1.0 op_sel_hi:[1,0]
	v_pk_add_f32 v[172:173], v[172:173], 1.0 op_sel_hi:[1,0]
	v_pk_add_f32 v[174:175], v[174:175], 1.0 op_sel_hi:[1,0]
	v_rcp_f32_e32 v168, v168
	v_rcp_f32_e32 v169, v169
	v_rcp_f32_e32 v170, v170
	v_rcp_f32_e32 v171, v171
	v_rcp_f32_e32 v172, v172
	v_rcp_f32_e32 v173, v173
	v_rcp_f32_e32 v174, v174
	v_rcp_f32_e32 v175, v175
	v_pk_mul_f32 v[30:31], v[30:31], v[168:169]
	v_pk_mul_f32 v[32:33], v[32:33], v[170:171]
	v_pk_mul_f32 v[22:23], v[22:23], v[172:173]
	v_pk_mul_f32 v[24:25], v[24:25], v[174:175]
	v_pk_mul_f32 v[30:31], v[26:27], v[30:31]
	v_pk_mul_f32 v[32:33], v[28:29], v[32:33]
	v_pk_mul_f32 v[22:23], v[14:15], v[22:23]
	v_pk_mul_f32 v[24:25], v[16:17], v[24:25]
	v_cvt_pk_bf16_f32 v156, v30, v31
	v_cvt_pk_bf16_f32 v157, v32, v33
	v_cvt_pk_bf16_f32 v158, v22, v23
	v_cvt_pk_bf16_f32 v159, v24, v25
	global_store_dwordx4 v[164:165], v[156:159], off
	v_lshl_add_u64 v[164:165], v[164:165], 0, s[12:13]
	v_add_f32_e32 v166, v200, v201
	v_add_f32_e32 v167, v202, v203
	v_add_f32_e32 v166, v166, v167
	v_fmamk_f32 v166, v166, 0x3a800000, v231
	v_rsq_f32_e32 v166, v166
	s_nop 0
	v_pk_fma_f32 v[18:19], v[18:19], v[166:167], v[142:143] op_sel_hi:[1,0,1]
	v_pk_fma_f32 v[20:21], v[20:21], v[166:167], v[144:145] op_sel_hi:[1,0,1]
	v_pk_fma_f32 v[6:7], v[6:7], v[166:167], v[134:135] op_sel_hi:[1,0,1]
	v_pk_fma_f32 v[8:9], v[8:9], v[166:167], v[136:137] op_sel_hi:[1,0,1]
	v_pk_fma_f32 v[10:11], v[10:11], v[166:167], v[138:139] op_sel_hi:[1,0,1]
	v_pk_fma_f32 v[12:13], v[12:13], v[166:167], v[140:141] op_sel_hi:[1,0,1]
	v_pk_fma_f32 v[2:3], v[2:3], v[166:167], v[130:131] op_sel_hi:[1,0,1]
	v_pk_fma_f32 v[4:5], v[4:5], v[166:167], v[132:133] op_sel_hi:[1,0,1]
	v_pk_mul_f32 v[168:169], v[18:19], s[10:11] op_sel_hi:[1,0]
	v_pk_mul_f32 v[170:171], v[20:21], s[10:11] op_sel_hi:[1,0]
	v_pk_mul_f32 v[172:173], v[6:7], s[10:11] op_sel_hi:[1,0]
	v_pk_mul_f32 v[174:175], v[8:9], s[10:11] op_sel_hi:[1,0]
	v_exp_f32_e32 v168, v168
	v_exp_f32_e32 v169, v169
	v_exp_f32_e32 v170, v170
	v_exp_f32_e32 v171, v171
	v_exp_f32_e32 v172, v172
	v_exp_f32_e32 v173, v173
	v_exp_f32_e32 v174, v174
	v_exp_f32_e32 v175, v175
	v_pk_add_f32 v[168:169], v[168:169], 1.0 op_sel_hi:[1,0]
	v_pk_add_f32 v[170:171], v[170:171], 1.0 op_sel_hi:[1,0]
	v_pk_add_f32 v[172:173], v[172:173], 1.0 op_sel_hi:[1,0]
	v_pk_add_f32 v[174:175], v[174:175], 1.0 op_sel_hi:[1,0]
	v_rcp_f32_e32 v168, v168
	v_rcp_f32_e32 v169, v169
	v_rcp_f32_e32 v170, v170
	v_rcp_f32_e32 v171, v171
	v_rcp_f32_e32 v172, v172
	v_rcp_f32_e32 v173, v173
	v_rcp_f32_e32 v174, v174
	v_rcp_f32_e32 v175, v175
	v_pk_mul_f32 v[18:19], v[18:19], v[168:169]
	v_pk_mul_f32 v[20:21], v[20:21], v[170:171]
	v_pk_mul_f32 v[6:7], v[6:7], v[172:173]
	v_pk_mul_f32 v[8:9], v[8:9], v[174:175]
	v_pk_mul_f32 v[18:19], v[10:11], v[18:19]
	v_pk_mul_f32 v[20:21], v[12:13], v[20:21]
	v_pk_mul_f32 v[6:7], v[2:3], v[6:7]
	v_pk_mul_f32 v[8:9], v[4:5], v[8:9]
	v_cvt_pk_bf16_f32 v156, v18, v19
	v_cvt_pk_bf16_f32 v157, v20, v21
	v_cvt_pk_bf16_f32 v158, v6, v7
	v_cvt_pk_bf16_f32 v159, v8, v9
	global_store_dwordx4 v[164:165], v[156:159], off
	v_lshl_add_u64 v[164:165], v[164:165], 0, s[12:13]
	v_add_f32_e32 v166, v204, v205
	v_add_f32_e32 v167, v206, v207
	v_add_f32_e32 v166, v166, v167
	v_fmamk_f32 v166, v166, 0x3a800000, v231
	v_rsq_f32_e32 v166, v166
	s_nop 0
	v_pk_fma_f32 v[126:127], v[126:127], v[166:167], v[142:143] op_sel_hi:[1,0,1]
	v_pk_fma_f32 v[128:129], v[128:129], v[166:167], v[144:145] op_sel_hi:[1,0,1]
	v_pk_fma_f32 v[118:119], v[118:119], v[166:167], v[134:135] op_sel_hi:[1,0,1]
	v_pk_fma_f32 v[120:121], v[120:121], v[166:167], v[136:137] op_sel_hi:[1,0,1]
	v_pk_fma_f32 v[122:123], v[122:123], v[166:167], v[138:139] op_sel_hi:[1,0,1]
	v_pk_fma_f32 v[124:125], v[124:125], v[166:167], v[140:141] op_sel_hi:[1,0,1]
	v_pk_fma_f32 v[114:115], v[114:115], v[166:167], v[130:131] op_sel_hi:[1,0,1]
	v_pk_fma_f32 v[116:117], v[116:117], v[166:167], v[132:133] op_sel_hi:[1,0,1]
	v_pk_mul_f32 v[168:169], v[126:127], s[10:11] op_sel_hi:[1,0]
	v_pk_mul_f32 v[170:171], v[128:129], s[10:11] op_sel_hi:[1,0]
	v_pk_mul_f32 v[172:173], v[118:119], s[10:11] op_sel_hi:[1,0]
	v_pk_mul_f32 v[174:175], v[120:121], s[10:11] op_sel_hi:[1,0]
	v_exp_f32_e32 v168, v168
	v_exp_f32_e32 v169, v169
	v_exp_f32_e32 v170, v170
	v_exp_f32_e32 v171, v171
	v_exp_f32_e32 v172, v172
	v_exp_f32_e32 v173, v173
	v_exp_f32_e32 v174, v174
	v_exp_f32_e32 v175, v175
	v_pk_add_f32 v[168:169], v[168:169], 1.0 op_sel_hi:[1,0]
	v_pk_add_f32 v[170:171], v[170:171], 1.0 op_sel_hi:[1,0]
	v_pk_add_f32 v[172:173], v[172:173], 1.0 op_sel_hi:[1,0]
	v_pk_add_f32 v[174:175], v[174:175], 1.0 op_sel_hi:[1,0]
	v_rcp_f32_e32 v168, v168
	v_rcp_f32_e32 v169, v169
	v_rcp_f32_e32 v170, v170
	v_rcp_f32_e32 v171, v171
	v_rcp_f32_e32 v172, v172
	v_rcp_f32_e32 v173, v173
	v_rcp_f32_e32 v174, v174
	v_rcp_f32_e32 v175, v175
	v_pk_mul_f32 v[126:127], v[126:127], v[168:169]
	v_pk_mul_f32 v[128:129], v[128:129], v[170:171]
	v_pk_mul_f32 v[118:119], v[118:119], v[172:173]
	v_pk_mul_f32 v[120:121], v[120:121], v[174:175]
	v_pk_mul_f32 v[126:127], v[122:123], v[126:127]
	v_pk_mul_f32 v[128:129], v[124:125], v[128:129]
	v_pk_mul_f32 v[118:119], v[114:115], v[118:119]
	v_pk_mul_f32 v[120:121], v[116:117], v[120:121]
	v_cvt_pk_bf16_f32 v156, v126, v127
	v_cvt_pk_bf16_f32 v157, v128, v129
	v_cvt_pk_bf16_f32 v158, v118, v119
	v_cvt_pk_bf16_f32 v159, v120, v121
	global_store_dwordx4 v[164:165], v[156:159], off
	v_lshl_add_u64 v[164:165], v[164:165], 0, s[12:13]
	v_add_f32_e32 v166, v208, v209
	v_add_f32_e32 v167, v210, v211
	v_add_f32_e32 v166, v166, v167
	v_fmamk_f32 v166, v166, 0x3a800000, v231
	v_rsq_f32_e32 v166, v166
	s_nop 0
	v_pk_fma_f32 v[110:111], v[110:111], v[166:167], v[142:143] op_sel_hi:[1,0,1]
	v_pk_fma_f32 v[112:113], v[112:113], v[166:167], v[144:145] op_sel_hi:[1,0,1]
	v_pk_fma_f32 v[102:103], v[102:103], v[166:167], v[134:135] op_sel_hi:[1,0,1]
	v_pk_fma_f32 v[104:105], v[104:105], v[166:167], v[136:137] op_sel_hi:[1,0,1]
	v_pk_fma_f32 v[106:107], v[106:107], v[166:167], v[138:139] op_sel_hi:[1,0,1]
	v_pk_fma_f32 v[108:109], v[108:109], v[166:167], v[140:141] op_sel_hi:[1,0,1]
	v_pk_fma_f32 v[98:99], v[98:99], v[166:167], v[130:131] op_sel_hi:[1,0,1]
	v_pk_fma_f32 v[100:101], v[100:101], v[166:167], v[132:133] op_sel_hi:[1,0,1]
	v_pk_mul_f32 v[168:169], v[110:111], s[10:11] op_sel_hi:[1,0]
	v_pk_mul_f32 v[170:171], v[112:113], s[10:11] op_sel_hi:[1,0]
	v_pk_mul_f32 v[172:173], v[102:103], s[10:11] op_sel_hi:[1,0]
	v_pk_mul_f32 v[174:175], v[104:105], s[10:11] op_sel_hi:[1,0]
	v_exp_f32_e32 v168, v168
	v_exp_f32_e32 v169, v169
	v_exp_f32_e32 v170, v170
	v_exp_f32_e32 v171, v171
	v_exp_f32_e32 v172, v172
	v_exp_f32_e32 v173, v173
	v_exp_f32_e32 v174, v174
	v_exp_f32_e32 v175, v175
	v_pk_add_f32 v[168:169], v[168:169], 1.0 op_sel_hi:[1,0]
	v_pk_add_f32 v[170:171], v[170:171], 1.0 op_sel_hi:[1,0]
	v_pk_add_f32 v[172:173], v[172:173], 1.0 op_sel_hi:[1,0]
	v_pk_add_f32 v[174:175], v[174:175], 1.0 op_sel_hi:[1,0]
	v_rcp_f32_e32 v168, v168
	v_rcp_f32_e32 v169, v169
	v_rcp_f32_e32 v170, v170
	v_rcp_f32_e32 v171, v171
	v_rcp_f32_e32 v172, v172
	v_rcp_f32_e32 v173, v173
	v_rcp_f32_e32 v174, v174
	v_rcp_f32_e32 v175, v175
	v_pk_mul_f32 v[110:111], v[110:111], v[168:169]
	v_pk_mul_f32 v[112:113], v[112:113], v[170:171]
	v_pk_mul_f32 v[102:103], v[102:103], v[172:173]
	v_pk_mul_f32 v[104:105], v[104:105], v[174:175]
	v_pk_mul_f32 v[110:111], v[106:107], v[110:111]
	v_pk_mul_f32 v[112:113], v[108:109], v[112:113]
	v_pk_mul_f32 v[102:103], v[98:99], v[102:103]
	v_pk_mul_f32 v[104:105], v[100:101], v[104:105]
	v_cvt_pk_bf16_f32 v156, v110, v111
	v_cvt_pk_bf16_f32 v157, v112, v113
	v_cvt_pk_bf16_f32 v158, v102, v103
	v_cvt_pk_bf16_f32 v159, v104, v105
	global_store_dwordx4 v[164:165], v[156:159], off
	v_lshl_add_u64 v[164:165], v[164:165], 0, s[14:15]
	v_add_f32_e32 v166, v212, v213
	v_add_f32_e32 v167, v214, v215
	v_add_f32_e32 v166, v166, v167
	v_fmamk_f32 v166, v166, 0x3a800000, v231
	v_rsq_f32_e32 v166, v166
	s_nop 0
	v_pk_fma_f32 v[94:95], v[94:95], v[166:167], v[142:143] op_sel_hi:[1,0,1]
	v_pk_fma_f32 v[96:97], v[96:97], v[166:167], v[144:145] op_sel_hi:[1,0,1]
	v_pk_fma_f32 v[86:87], v[86:87], v[166:167], v[134:135] op_sel_hi:[1,0,1]
	v_pk_fma_f32 v[88:89], v[88:89], v[166:167], v[136:137] op_sel_hi:[1,0,1]
	v_pk_fma_f32 v[90:91], v[90:91], v[166:167], v[138:139] op_sel_hi:[1,0,1]
	v_pk_fma_f32 v[92:93], v[92:93], v[166:167], v[140:141] op_sel_hi:[1,0,1]
	v_pk_fma_f32 v[82:83], v[82:83], v[166:167], v[130:131] op_sel_hi:[1,0,1]
	v_pk_fma_f32 v[84:85], v[84:85], v[166:167], v[132:133] op_sel_hi:[1,0,1]
	v_pk_mul_f32 v[168:169], v[94:95], s[10:11] op_sel_hi:[1,0]
	v_pk_mul_f32 v[170:171], v[96:97], s[10:11] op_sel_hi:[1,0]
	v_pk_mul_f32 v[172:173], v[86:87], s[10:11] op_sel_hi:[1,0]
	v_pk_mul_f32 v[174:175], v[88:89], s[10:11] op_sel_hi:[1,0]
	v_exp_f32_e32 v168, v168
	v_exp_f32_e32 v169, v169
	v_exp_f32_e32 v170, v170
	v_exp_f32_e32 v171, v171
	v_exp_f32_e32 v172, v172
	v_exp_f32_e32 v173, v173
	v_exp_f32_e32 v174, v174
	v_exp_f32_e32 v175, v175
	v_pk_add_f32 v[168:169], v[168:169], 1.0 op_sel_hi:[1,0]
	v_pk_add_f32 v[170:171], v[170:171], 1.0 op_sel_hi:[1,0]
	v_pk_add_f32 v[172:173], v[172:173], 1.0 op_sel_hi:[1,0]
	v_pk_add_f32 v[174:175], v[174:175], 1.0 op_sel_hi:[1,0]
	v_rcp_f32_e32 v168, v168
	v_rcp_f32_e32 v169, v169
	v_rcp_f32_e32 v170, v170
	v_rcp_f32_e32 v171, v171
	v_rcp_f32_e32 v172, v172
	v_rcp_f32_e32 v173, v173
	v_rcp_f32_e32 v174, v174
	v_rcp_f32_e32 v175, v175
	v_pk_mul_f32 v[94:95], v[94:95], v[168:169]
	v_pk_mul_f32 v[96:97], v[96:97], v[170:171]
	v_pk_mul_f32 v[86:87], v[86:87], v[172:173]
	v_pk_mul_f32 v[88:89], v[88:89], v[174:175]
	v_pk_mul_f32 v[94:95], v[90:91], v[94:95]
	v_pk_mul_f32 v[96:97], v[92:93], v[96:97]
	v_pk_mul_f32 v[86:87], v[82:83], v[86:87]
	v_pk_mul_f32 v[88:89], v[84:85], v[88:89]
	v_cvt_pk_bf16_f32 v156, v94, v95
	v_cvt_pk_bf16_f32 v157, v96, v97
	v_cvt_pk_bf16_f32 v158, v86, v87
	v_cvt_pk_bf16_f32 v159, v88, v89
	global_store_dwordx4 v[164:165], v[156:159], off
	v_lshl_add_u64 v[164:165], v[164:165], 0, s[12:13]
	v_add_f32_e32 v166, v216, v217
	v_add_f32_e32 v167, v218, v219
	v_add_f32_e32 v166, v166, v167
	v_fmamk_f32 v166, v166, 0x3a800000, v231
	v_rsq_f32_e32 v166, v166
	s_nop 0
	v_pk_fma_f32 v[78:79], v[78:79], v[166:167], v[142:143] op_sel_hi:[1,0,1]
	v_pk_fma_f32 v[80:81], v[80:81], v[166:167], v[144:145] op_sel_hi:[1,0,1]
	v_pk_fma_f32 v[70:71], v[70:71], v[166:167], v[134:135] op_sel_hi:[1,0,1]
	v_pk_fma_f32 v[72:73], v[72:73], v[166:167], v[136:137] op_sel_hi:[1,0,1]
	v_pk_fma_f32 v[74:75], v[74:75], v[166:167], v[138:139] op_sel_hi:[1,0,1]
	v_pk_fma_f32 v[76:77], v[76:77], v[166:167], v[140:141] op_sel_hi:[1,0,1]
	v_pk_fma_f32 v[66:67], v[66:67], v[166:167], v[130:131] op_sel_hi:[1,0,1]
	v_pk_fma_f32 v[68:69], v[68:69], v[166:167], v[132:133] op_sel_hi:[1,0,1]
	v_pk_mul_f32 v[168:169], v[78:79], s[10:11] op_sel_hi:[1,0]
	v_pk_mul_f32 v[170:171], v[80:81], s[10:11] op_sel_hi:[1,0]
	v_pk_mul_f32 v[172:173], v[70:71], s[10:11] op_sel_hi:[1,0]
	v_pk_mul_f32 v[174:175], v[72:73], s[10:11] op_sel_hi:[1,0]
	v_exp_f32_e32 v168, v168
	v_exp_f32_e32 v169, v169
	v_exp_f32_e32 v170, v170
	v_exp_f32_e32 v171, v171
	v_exp_f32_e32 v172, v172
	v_exp_f32_e32 v173, v173
	v_exp_f32_e32 v174, v174
	v_exp_f32_e32 v175, v175
	v_pk_add_f32 v[168:169], v[168:169], 1.0 op_sel_hi:[1,0]
	v_pk_add_f32 v[170:171], v[170:171], 1.0 op_sel_hi:[1,0]
	v_pk_add_f32 v[172:173], v[172:173], 1.0 op_sel_hi:[1,0]
	v_pk_add_f32 v[174:175], v[174:175], 1.0 op_sel_hi:[1,0]
	v_rcp_f32_e32 v168, v168
	v_rcp_f32_e32 v169, v169
	v_rcp_f32_e32 v170, v170
	v_rcp_f32_e32 v171, v171
	v_rcp_f32_e32 v172, v172
	v_rcp_f32_e32 v173, v173
	v_rcp_f32_e32 v174, v174
	v_rcp_f32_e32 v175, v175
	v_pk_mul_f32 v[78:79], v[78:79], v[168:169]
	v_pk_mul_f32 v[80:81], v[80:81], v[170:171]
	v_pk_mul_f32 v[70:71], v[70:71], v[172:173]
	v_pk_mul_f32 v[72:73], v[72:73], v[174:175]
	v_pk_mul_f32 v[78:79], v[74:75], v[78:79]
	v_pk_mul_f32 v[80:81], v[76:77], v[80:81]
	v_pk_mul_f32 v[70:71], v[66:67], v[70:71]
	v_pk_mul_f32 v[72:73], v[68:69], v[72:73]
	v_cvt_pk_bf16_f32 v156, v78, v79
	v_cvt_pk_bf16_f32 v157, v80, v81
	v_cvt_pk_bf16_f32 v158, v70, v71
	v_cvt_pk_bf16_f32 v159, v72, v73
	global_store_dwordx4 v[164:165], v[156:159], off
	v_lshl_add_u64 v[164:165], v[164:165], 0, s[12:13]
	v_add_f32_e32 v166, v220, v221
	v_add_f32_e32 v167, v222, v223
	v_add_f32_e32 v166, v166, v167
	v_fmamk_f32 v166, v166, 0x3a800000, v231
	v_rsq_f32_e32 v166, v166
	s_nop 0
	v_pk_fma_f32 v[62:63], v[62:63], v[166:167], v[142:143] op_sel_hi:[1,0,1]
	v_pk_fma_f32 v[64:65], v[64:65], v[166:167], v[144:145] op_sel_hi:[1,0,1]
	v_pk_fma_f32 v[54:55], v[54:55], v[166:167], v[134:135] op_sel_hi:[1,0,1]
	v_pk_fma_f32 v[56:57], v[56:57], v[166:167], v[136:137] op_sel_hi:[1,0,1]
	v_pk_fma_f32 v[58:59], v[58:59], v[166:167], v[138:139] op_sel_hi:[1,0,1]
	v_pk_fma_f32 v[60:61], v[60:61], v[166:167], v[140:141] op_sel_hi:[1,0,1]
	v_pk_fma_f32 v[50:51], v[50:51], v[166:167], v[130:131] op_sel_hi:[1,0,1]
	v_pk_fma_f32 v[52:53], v[52:53], v[166:167], v[132:133] op_sel_hi:[1,0,1]
	v_pk_mul_f32 v[168:169], v[62:63], s[10:11] op_sel_hi:[1,0]
	v_pk_mul_f32 v[170:171], v[64:65], s[10:11] op_sel_hi:[1,0]
	v_pk_mul_f32 v[172:173], v[54:55], s[10:11] op_sel_hi:[1,0]
	v_pk_mul_f32 v[174:175], v[56:57], s[10:11] op_sel_hi:[1,0]
	v_exp_f32_e32 v168, v168
	v_exp_f32_e32 v169, v169
	v_exp_f32_e32 v170, v170
	v_exp_f32_e32 v171, v171
	v_exp_f32_e32 v172, v172
	v_exp_f32_e32 v173, v173
	v_exp_f32_e32 v174, v174
	v_exp_f32_e32 v175, v175
	v_pk_add_f32 v[168:169], v[168:169], 1.0 op_sel_hi:[1,0]
	v_pk_add_f32 v[170:171], v[170:171], 1.0 op_sel_hi:[1,0]
	v_pk_add_f32 v[172:173], v[172:173], 1.0 op_sel_hi:[1,0]
	v_pk_add_f32 v[174:175], v[174:175], 1.0 op_sel_hi:[1,0]
	v_rcp_f32_e32 v168, v168
	v_rcp_f32_e32 v169, v169
	v_rcp_f32_e32 v170, v170
	v_rcp_f32_e32 v171, v171
	v_rcp_f32_e32 v172, v172
	v_rcp_f32_e32 v173, v173
	v_rcp_f32_e32 v174, v174
	v_rcp_f32_e32 v175, v175
	v_pk_mul_f32 v[62:63], v[62:63], v[168:169]
	v_pk_mul_f32 v[64:65], v[64:65], v[170:171]
	v_pk_mul_f32 v[54:55], v[54:55], v[172:173]
	v_pk_mul_f32 v[56:57], v[56:57], v[174:175]
	v_pk_mul_f32 v[62:63], v[58:59], v[62:63]
	v_pk_mul_f32 v[64:65], v[60:61], v[64:65]
	v_pk_mul_f32 v[54:55], v[50:51], v[54:55]
	v_pk_mul_f32 v[56:57], v[52:53], v[56:57]
	v_cvt_pk_bf16_f32 v156, v62, v63
	v_cvt_pk_bf16_f32 v157, v64, v65
	v_cvt_pk_bf16_f32 v158, v54, v55
	v_cvt_pk_bf16_f32 v159, v56, v57
	global_store_dwordx4 v[164:165], v[156:159], off
	v_lshl_add_u64 v[164:165], v[164:165], 0, s[12:13]
	v_add_f32_e32 v166, v224, v225
	v_add_f32_e32 v167, v226, v227
	v_add_f32_e32 v166, v166, v167
	v_fmamk_f32 v166, v166, 0x3a800000, v231
	v_rsq_f32_e32 v166, v166
	s_nop 0
	v_pk_fma_f32 v[46:47], v[46:47], v[166:167], v[142:143] op_sel_hi:[1,0,1]
	v_pk_fma_f32 v[48:49], v[48:49], v[166:167], v[144:145] op_sel_hi:[1,0,1]
	v_pk_fma_f32 v[38:39], v[38:39], v[166:167], v[134:135] op_sel_hi:[1,0,1]
	v_pk_fma_f32 v[40:41], v[40:41], v[166:167], v[136:137] op_sel_hi:[1,0,1]
	v_pk_fma_f32 v[42:43], v[42:43], v[166:167], v[138:139] op_sel_hi:[1,0,1]
	v_pk_fma_f32 v[44:45], v[44:45], v[166:167], v[140:141] op_sel_hi:[1,0,1]
	v_pk_fma_f32 v[34:35], v[34:35], v[166:167], v[130:131] op_sel_hi:[1,0,1]
	v_pk_fma_f32 v[36:37], v[36:37], v[166:167], v[132:133] op_sel_hi:[1,0,1]
	v_pk_mul_f32 v[168:169], v[46:47], s[10:11] op_sel_hi:[1,0]
	v_pk_mul_f32 v[170:171], v[48:49], s[10:11] op_sel_hi:[1,0]
	v_pk_mul_f32 v[172:173], v[38:39], s[10:11] op_sel_hi:[1,0]
	v_pk_mul_f32 v[174:175], v[40:41], s[10:11] op_sel_hi:[1,0]
	v_exp_f32_e32 v168, v168
	v_exp_f32_e32 v169, v169
	v_exp_f32_e32 v170, v170
	v_exp_f32_e32 v171, v171
	v_exp_f32_e32 v172, v172
	v_exp_f32_e32 v173, v173
	v_exp_f32_e32 v174, v174
	v_exp_f32_e32 v175, v175
	v_pk_add_f32 v[168:169], v[168:169], 1.0 op_sel_hi:[1,0]
	v_pk_add_f32 v[170:171], v[170:171], 1.0 op_sel_hi:[1,0]
	v_pk_add_f32 v[172:173], v[172:173], 1.0 op_sel_hi:[1,0]
	v_pk_add_f32 v[174:175], v[174:175], 1.0 op_sel_hi:[1,0]
	v_rcp_f32_e32 v168, v168
	v_rcp_f32_e32 v169, v169
	v_rcp_f32_e32 v170, v170
	v_rcp_f32_e32 v171, v171
	v_rcp_f32_e32 v172, v172
	v_rcp_f32_e32 v173, v173
	v_rcp_f32_e32 v174, v174
	v_rcp_f32_e32 v175, v175
	v_pk_mul_f32 v[46:47], v[46:47], v[168:169]
	v_pk_mul_f32 v[48:49], v[48:49], v[170:171]
	v_pk_mul_f32 v[38:39], v[38:39], v[172:173]
	v_pk_mul_f32 v[40:41], v[40:41], v[174:175]
	v_pk_mul_f32 v[46:47], v[42:43], v[46:47]
	v_pk_mul_f32 v[48:49], v[44:45], v[48:49]
	v_pk_mul_f32 v[38:39], v[34:35], v[38:39]
	v_pk_mul_f32 v[40:41], v[36:37], v[40:41]
	v_cvt_pk_bf16_f32 v156, v46, v47
	v_cvt_pk_bf16_f32 v157, v48, v49
	v_cvt_pk_bf16_f32 v158, v38, v39
	v_cvt_pk_bf16_f32 v159, v40, v41
	global_store_dwordx4 v[164:165], v[156:159], off
